# adaLN finalize (P1): the 32 partial-sum loads issued together instead of 8 serialized rounds of 4
# speedup vs baseline: 1.0094x; 1.0094x over previous
; __global__ void __launch_bounds__(512, 2) fwd_mega(Args args) {
;     ...
;         for (int i = bx * 512 + tid; i < 5 * NMOD; i += G * 512) { const int v = i / NMOD, n = i % NMOD; float s = b_ada[n];
;             for (int kp = 0; kp < 32; ++kp) s += part[(size_t)(kp * 5 + v) * NMOD + n];
;             modall[i] = s; }
.LBB0_119:
	v_mul_hi_i32 v3, v2, s6
	v_lshrrev_b32_e32 v4, 31, v3
	v_ashrrev_i32_e32 v3, 11, v3
	v_add_u32_e32 v3, v3, v4
	v_mul_i32_i24_e32 v4, 0x3000, v3
	v_sub_u32_e32 v4, v2, v4
	v_ashrrev_i32_e32 v5, 31, v4
	v_lshlrev_b64 v[4:5], 2, v[4:5]
	v_lshl_add_u64 v[6:7], s[90:91], 0, v[4:5]
	global_load_dword v6, v[6:7], off
	v_mad_i64_i32 v[4:5], s[18:19], v3, s7, v[4:5]
	v_lshl_add_u64 v[4:5], s[14:15], 0, v[4:5]
	s_mov_b64 s[22:23], 0x100000
	v_lshl_add_u64 v[8:9], v[4:5], 0, s[22:23]
	s_mov_b64 s[22:23], 0x3c000
	global_load_dword v16, v[8:9], off
	v_lshl_add_u64 v[8:9], v[8:9], 0, s[22:23]
	global_load_dword v17, v[8:9], off
	v_lshl_add_u64 v[8:9], v[8:9], 0, s[22:23]
	global_load_dword v18, v[8:9], off
	v_lshl_add_u64 v[8:9], v[8:9], 0, s[22:23]
	global_load_dword v19, v[8:9], off
	v_lshl_add_u64 v[8:9], v[8:9], 0, s[22:23]
	global_load_dword v20, v[8:9], off
	v_lshl_add_u64 v[8:9], v[8:9], 0, s[22:23]
	global_load_dword v21, v[8:9], off
	v_lshl_add_u64 v[8:9], v[8:9], 0, s[22:23]
	global_load_dword v22, v[8:9], off
	v_lshl_add_u64 v[8:9], v[8:9], 0, s[22:23]
	global_load_dword v23, v[8:9], off
	v_lshl_add_u64 v[8:9], v[8:9], 0, s[22:23]
	global_load_dword v24, v[8:9], off
	v_lshl_add_u64 v[8:9], v[8:9], 0, s[22:23]
	global_load_dword v25, v[8:9], off
	v_lshl_add_u64 v[8:9], v[8:9], 0, s[22:23]
	global_load_dword v26, v[8:9], off
	v_lshl_add_u64 v[8:9], v[8:9], 0, s[22:23]
	global_load_dword v27, v[8:9], off
	v_lshl_add_u64 v[8:9], v[8:9], 0, s[22:23]
	global_load_dword v28, v[8:9], off
	v_lshl_add_u64 v[8:9], v[8:9], 0, s[22:23]
	global_load_dword v29, v[8:9], off
	v_lshl_add_u64 v[8:9], v[8:9], 0, s[22:23]
	global_load_dword v30, v[8:9], off
	v_lshl_add_u64 v[8:9], v[8:9], 0, s[22:23]
	global_load_dword v31, v[8:9], off
	v_lshl_add_u64 v[8:9], v[8:9], 0, s[22:23]
	global_load_dword v32, v[8:9], off
	v_lshl_add_u64 v[8:9], v[8:9], 0, s[22:23]
	global_load_dword v33, v[8:9], off
	v_lshl_add_u64 v[8:9], v[8:9], 0, s[22:23]
	global_load_dword v34, v[8:9], off
	v_lshl_add_u64 v[8:9], v[8:9], 0, s[22:23]
	global_load_dword v35, v[8:9], off
	v_lshl_add_u64 v[8:9], v[8:9], 0, s[22:23]
	global_load_dword v36, v[8:9], off
	v_lshl_add_u64 v[8:9], v[8:9], 0, s[22:23]
	global_load_dword v37, v[8:9], off
	v_lshl_add_u64 v[8:9], v[8:9], 0, s[22:23]
	global_load_dword v38, v[8:9], off
	v_lshl_add_u64 v[8:9], v[8:9], 0, s[22:23]
	global_load_dword v39, v[8:9], off
	v_lshl_add_u64 v[8:9], v[8:9], 0, s[22:23]
	global_load_dword v40, v[8:9], off
	v_lshl_add_u64 v[8:9], v[8:9], 0, s[22:23]
	global_load_dword v41, v[8:9], off
	v_lshl_add_u64 v[8:9], v[8:9], 0, s[22:23]
	global_load_dword v42, v[8:9], off
	v_lshl_add_u64 v[8:9], v[8:9], 0, s[22:23]
	global_load_dword v43, v[8:9], off
	v_lshl_add_u64 v[8:9], v[8:9], 0, s[22:23]
	global_load_dword v44, v[8:9], off
	v_lshl_add_u64 v[8:9], v[8:9], 0, s[22:23]
	global_load_dword v45, v[8:9], off
	v_lshl_add_u64 v[8:9], v[8:9], 0, s[22:23]
	global_load_dword v46, v[8:9], off
	v_lshl_add_u64 v[8:9], v[8:9], 0, s[22:23]
	global_load_dword v47, v[8:9], off
	s_waitcnt vmcnt(31)
	v_add_f32_e32 v6, v6, v16
	s_waitcnt vmcnt(30)
	v_add_f32_e32 v6, v6, v17
	s_waitcnt vmcnt(29)
	v_add_f32_e32 v6, v6, v18
	s_waitcnt vmcnt(28)
	v_add_f32_e32 v6, v6, v19
	s_waitcnt vmcnt(27)
	v_add_f32_e32 v6, v6, v20
	s_waitcnt vmcnt(26)
	v_add_f32_e32 v6, v6, v21
	s_waitcnt vmcnt(25)
	v_add_f32_e32 v6, v6, v22
	s_waitcnt vmcnt(24)
	v_add_f32_e32 v6, v6, v23
	s_waitcnt vmcnt(23)
	v_add_f32_e32 v6, v6, v24
	s_waitcnt vmcnt(22)
	v_add_f32_e32 v6, v6, v25
	s_waitcnt vmcnt(21)
	v_add_f32_e32 v6, v6, v26
	s_waitcnt vmcnt(20)
	v_add_f32_e32 v6, v6, v27
	s_waitcnt vmcnt(19)
	v_add_f32_e32 v6, v6, v28
	s_waitcnt vmcnt(18)
	v_add_f32_e32 v6, v6, v29
	s_waitcnt vmcnt(17)
	v_add_f32_e32 v6, v6, v30
	s_waitcnt vmcnt(16)
	v_add_f32_e32 v6, v6, v31
	s_waitcnt vmcnt(15)
	v_add_f32_e32 v6, v6, v32
	s_waitcnt vmcnt(14)
	v_add_f32_e32 v6, v6, v33
	s_waitcnt vmcnt(13)
	v_add_f32_e32 v6, v6, v34
	s_waitcnt vmcnt(12)
	v_add_f32_e32 v6, v6, v35
	s_waitcnt vmcnt(11)
	v_add_f32_e32 v6, v6, v36
	s_waitcnt vmcnt(10)
	v_add_f32_e32 v6, v6, v37
	s_waitcnt vmcnt(9)
	v_add_f32_e32 v6, v6, v38
	s_waitcnt vmcnt(8)
	v_add_f32_e32 v6, v6, v39
	s_waitcnt vmcnt(7)
	v_add_f32_e32 v6, v6, v40
	s_waitcnt vmcnt(6)
	v_add_f32_e32 v6, v6, v41
	s_waitcnt vmcnt(5)
	v_add_f32_e32 v6, v6, v42
	s_waitcnt vmcnt(4)
	v_add_f32_e32 v6, v6, v43
	s_waitcnt vmcnt(3)
	v_add_f32_e32 v6, v6, v44
	s_waitcnt vmcnt(2)
	v_add_f32_e32 v6, v6, v45
	s_waitcnt vmcnt(1)
	v_add_f32_e32 v6, v6, v46
	s_waitcnt vmcnt(0)
	v_add_f32_e32 v6, v6, v47
	v_ashrrev_i32_e32 v3, 31, v2
	v_lshl_add_u64 v[4:5], v[2:3], 2, s[14:15]
	v_add_u32_e32 v2, s3, v2
	v_cmp_lt_i32_e32 vcc, s16, v2
	s_or_b64 s[8:9], vcc, s[8:9]
	global_store_dword v[4:5], v6, off
	s_andn2_b64 exec, exec, s[8:9]
	s_cbranch_execnz .LBB0_119
